# G9 tail round (layer 0: 32 ctx units) split into 64 half-units (128-row halves) on 64 CUs: K-loop skips the other half's MMA blocks, epilogue skips its row groups
# baseline (speedup 1.0000x reference)
; DI void layer_body(Frame& F, const int l) {
;     ...
;         { pg8::Gemm g{(const bf16_t*)(F.ws + WS_ACT), (const bf16_t*)(F.ws + WS_WDN) + (size_t)l * D * DFF, DFF, DFF, DFF, 0};
;           pg8::Sched S; S.init(Mq / 256, 8, F.G, F.vcu, 0);
.LBB0_1691:
	s_mov_b32 s32, 0
	s_mov_b32 s46, s69
	s_movk_i32 s50, 0x3f80
	s_movk_i32 s51, 0x3f70
	s_movk_i32 s69, 0x3f60
	s_movk_i32 s83, 0x3f50
	s_movk_i32 s63, 0x1a00
	s_movk_i32 s84, 0x3fff
	s_movk_i32 s85, 0x2200
	s_movk_i32 s67, 0x7ff
	s_movk_i32 s45, 0x1600
	s_mov_b32 s6, s46
	s_cmp_gt_i32 s46, -1
	s_mov_b32 s14, 0
	s_cbranch_scc1 .LBB0_1693
	s_abs_i32 s0, s64
	v_cvt_f32_u32_e32 v0, s0
	s_sub_i32 s2, 0, s0
	s_not_b32 s1, s6
	s_add_i32 s1, s64, s1
	v_rcp_iflag_f32_e32 v0, v0
	s_xor_b32 s3, s1, s64
	s_abs_i32 s1, s1
	s_ashr_i32 s3, s3, 31
	v_mul_f32_e32 v0, 0x4f7ffffe, v0
	v_cvt_u32_f32_e32 v0, v0
	s_nop 0
	v_readfirstlane_b32 s4, v0
	s_mul_i32 s2, s2, s4
	s_mul_hi_u32 s2, s4, s2
	s_add_i32 s4, s4, s2
	s_mul_hi_u32 s2, s1, s4
	s_mul_i32 s4, s2, s0
	s_sub_i32 s1, s1, s4
	s_add_i32 s5, s2, 1
	s_sub_i32 s4, s1, s0
	s_cmp_ge_u32 s1, s0
	s_cselect_b32 s2, s5, s2
	s_cselect_b32 s1, s4, s1
	s_add_i32 s4, s2, 1
	s_cmp_ge_u32 s1, s0
	s_cselect_b32 s0, s4, s2
	s_xor_b32 s0, s0, s3
	s_sub_i32 s14, s0, s3

;     DI bool next(int i, Unit& u) const { const int L = (i0 + i) * G + c - start; if (L >= 144) return false; const int bt = L >> 2; u.pm = L & 3; u.pn = (bt / 9) * 16 + (bt % 9); u.kob = 256 * u.pm; return true; }
;     DI bool next(int i, Unit& u) const {
;         const long L = (long)(i0 + i) * G + c - start; if (L >= cnt) return false;
;         const int w = (int)L, nig = 8 * nN, gid = w / nig, fm = gid * 8, gsz = (nM - fm) < 8 ? (nM - fm) : 8;
;         u.pm = fm + ((w % nig) % gsz); u.pn = (w % nig) / gsz; u.kob = kobm * u.pm; return true;
;     }
; template <class Epi, class SchedT>
; DI void gemm_phase(LAS unsigned char* lds, const Gemm g, const SchedT& S, const Epi& E) {
;     ...
;         const bool has_next = S.next(ui + 1, nxt);
;         const char* nA = has_next ? (const char*)g.A + (size_t)nxt.pm * tstepA : cA; const char* nB = has_next ? (const char*)g.Bt + (size_t)nxt.pn * tstepB + (size_t)nxt.kob * 2 : cB;
.LBB0_1697:
	s_mov_b32 s32, s100
	s_andn2_b64 vcc, exec, s[8:9]
	s_mov_b32 s33, s36
	s_mov_b32 s38, s37
	s_mov_b64 s[10:11], s[0:1]
	s_mov_b64 s[8:9], s[6:7]
	s_cbranch_vccz .LBB0_1708
.LBB0_1698:
	s_add_i32 s35, s35, 1
	s_add_i32 s0, s35, s14
	s_mul_hi_i32 s1, s0, s64
	s_mul_i32 s0, s0, s64
	s_add_u32 s0, s0, s46
	s_addc_u32 s1, s1, s16
	s_mov_b32 s100, 0
	s_cmp_lg_u32 s64, 0x100
	s_cbranch_scc1 .Lg9_nosplit
	s_cmp_lg_u32 s1, 0
	s_cbranch_scc1 .Lg9_nosplit
	s_and_b32 s98, s56, 0xffffff00
	s_sub_u32 s99, s56, s98
	s_cmp_eq_u32 s99, 0
	s_cbranch_scc1 .Lg9_nosplit
	s_cmp_gt_u32 s99, 0x80
	s_cbranch_scc1 .Lg9_nosplit
	s_cmp_lt_u32 s0, s98
	s_cbranch_scc1 .Lg9_nosplit
	s_sub_u32 s99, s0, s98
	s_and_b32 s100, s99, 1
	s_add_u32 s100, s100, 1
	s_lshr_b32 s99, s99, 1
	s_add_u32 s0, s98, s99
.Lg9_nosplit:
	v_mov_b64_e32 v[2:3], s[56:57]
	v_cmp_ge_i64_e32 vcc, s[0:1], v[2:3]
	v_cmp_lt_i64_e64 s[2:3], s[0:1], v[2:3]
	s_cbranch_vccnz .LBB0_1700
	s_ashr_i32 s1, s0, 31
	s_lshr_b32 s1, s1, 26
	s_add_i32 s1, s0, s1
	s_ashr_i32 s6, s1, 6
	s_lshl_b32 s6, s6, 3
	s_sub_i32 s7, s23, s6
	s_min_i32 s7, s7, 8
	s_abs_i32 s12, s7
	v_cvt_f32_u32_e32 v2, s12
	s_sub_i32 s36, 0, s12
	s_andn2_b32 s1, s1, 63
	s_sub_i32 s0, s0, s1
	v_rcp_iflag_f32_e32 v2, v2
	s_abs_i32 s1, s0
	s_xor_b32 s13, s0, s7
	s_ashr_i32 s13, s13, 31
	v_mul_f32_e32 v2, 0x4f7ffffe, v2
	v_cvt_u32_f32_e32 v2, v2
	s_nop 0
	v_readfirstlane_b32 s37, v2
	s_mul_i32 s36, s36, s37
	s_mul_hi_u32 s36, s37, s36
	s_add_i32 s37, s37, s36
	s_mul_hi_u32 s36, s1, s37
	s_mul_i32 s37, s36, s12
	s_sub_i32 s1, s1, s37
	s_add_i32 s39, s36, 1
	s_sub_i32 s37, s1, s12
	s_cmp_ge_u32 s1, s12
	s_cselect_b32 s36, s39, s36
	s_cselect_b32 s1, s37, s1
	s_add_i32 s37, s36, 1
	s_cmp_ge_u32 s1, s12
	s_cselect_b32 s1, s37, s36
	s_xor_b32 s1, s1, s13
	s_sub_i32 s36, s1, s13
	s_mul_i32 s1, s36, s7
	s_sub_i32 s0, s0, s1
	s_add_i32 s37, s0, s6

; #define PG8_STAGE(bufoff, gbase, voff) do { _Pragma("unroll") for (int _i = 0; _i < 2; ++_i) \
;         __builtin_amdgcn_global_load_lds((const unsigned*)((const char*)(gbase) + (voff)[_i]), (LAS unsigned*)(lds + (bufoff) + ldsw + _i * 8192), 16, 0, 0); } while (0)
; #define PG8_LDA(dst, b, h) do { _Pragma("unroll") for (int m = 0; m < 4; ++m) _Pragma("unroll") for (int k = 0; k < 2; ++k) dst[m][k] = *(const LAS bf16x8*)(lds + PG8_SA(b, h) + aoff + m * 2048 + k * 1024); } while (0)
; #define PG8_LDB(dst, b, h) do { _Pragma("unroll") for (int n = 0; n < 2; ++n) _Pragma("unroll") for (int k = 0; k < 2; ++k) dst[n][k] = *(const LAS bf16x8*)(lds + PG8_SB(b, h) + boff + n * 2048 + k * 1024); } while (0)
; #define PG8_MMA(ai, bj, At, Bt) do { __builtin_amdgcn_s_setprio(1); _Pragma("unroll") for (int m = 0; m < 4; ++m) _Pragma("unroll") for (int n = 0; n < 2; ++n) _Pragma("unroll") for (int k = 0; k < 2; ++k) \
;         acc[ai][bj][m][n] = __builtin_amdgcn_mfma_f32_16x16x32_bf16(Bt[n][k], At[m][k], acc[ai][bj][m][n], 0, 0, 0); __builtin_amdgcn_s_setprio(0); } while (0)
; #define PG8_WAIT_L(n) asm volatile("s_waitcnt lgkmcnt(" #n ")" ::: "memory")
; #define PG8_BAR __builtin_amdgcn_s_barrier()
; #define PG8_SCHED __builtin_amdgcn_sched_barrier(0)
; template <class Epi, class SchedT>
; DI void gemm_phase(LAS unsigned char* lds, const Gemm g, const SchedT& S, const Epi& E) {
;     ...
;             PG8_LDB(B0, 0, 0); PG8_SCHED; PG8_LDA(At, 0, 0); PG8_STAGE(PG8_SA(1, 1), a1 + hstepA, voffA);
;             PG8_WAIT_L(8); PG8_BAR; PG8_WAIT_L(0); PG8_MMA(0, 0, At, B0); PG8_BAR; PG8_SCHED;
;             PG8_LDB(B1, 0, 1); PG8_STAGE(PG8_SB(0, 0), b2, voffB);
;             PG8_BAR; PG8_WAIT_L(0); PG8_MMA(0, 1, At, B1); PG8_BAR;
;             PG8_LDA(At, 0, 1); PG8_STAGE(PG8_SA(0, 0), a2, voffA);
;             PG8_BAR; PG8_WAIT_L(0); PG8_MMA(1, 0, At, B0); PG8_BAR; PG8_SCHED;
.LBB0_1705:
	s_add_u32 s10, s8, 0xffea0080
	s_addc_u32 s11, s9, -1
	s_add_i32 s42, 0, 0x10000
	v_add_u32_e32 v36, s42, v150
	ds_read_b128 v[46:49], v36
	ds_read_b128 v[54:57], v36 offset:1024
	ds_read_b128 v[62:65], v36 offset:2048
	ds_read_b128 v[152:155], v36 offset:3072
	s_cmpk_eq_i32 s41, 0x54
	s_cselect_b32 s13, s7, s11
	s_cselect_b32 s12, s6, s10
	s_cselect_b32 s11, s1, s40
	s_cselect_b32 s10, s0, s39
	v_lshl_add_u64 v[36:37], s[8:9], 0, v[0:1]
	s_add_i32 m0, s24, 0xc000
	ds_read_b128 v[156:159], v151
	ds_read_b128 v[160:163], v151 offset:1024
	ds_read_b128 v[164:167], v151 offset:2048
	ds_read_b128 v[168:171], v151 offset:3072
	ds_read_b128 v[172:175], v151 offset:4096
	ds_read_b128 v[176:179], v151 offset:5120
	ds_read_b128 v[184:187], v151 offset:6144
	ds_read_b128 v[188:191], v151 offset:7168
	global_load_lds_dwordx4 v[36:37], off
	v_lshl_add_u64 v[36:37], s[8:9], 0, v[34:35]
	s_add_i32 m0, s24, 0xe000
	s_nop 0
	global_load_lds_dwordx4 v[36:37], off
	s_waitcnt lgkmcnt(8)
	s_barrier
	s_waitcnt lgkmcnt(0)
	s_cmp_eq_u32 s32, 2
	s_cbranch_scc1 .Lg9_skip_0
	s_setprio 1
	s_waitcnt lgkmcnt(0)
	v_mfma_f32_16x16x32_bf16 v[142:145], v[46:49], v[156:159], v[142:145]
	v_mfma_f32_16x16x32_bf16 v[138:141], v[62:65], v[156:159], v[138:141]
	v_mfma_f32_16x16x32_bf16 v[126:129], v[46:49], v[164:167], v[126:129]
	v_mfma_f32_16x16x32_bf16 v[122:125], v[62:65], v[164:167], v[122:125]
	v_mfma_f32_16x16x32_bf16 v[110:113], v[46:49], v[172:175], v[110:113]
	v_mfma_f32_16x16x32_bf16 v[106:109], v[62:65], v[172:175], v[106:109]
	v_mfma_f32_16x16x32_bf16 v[94:97], v[46:49], v[184:187], v[94:97]
	v_mfma_f32_16x16x32_bf16 v[90:93], v[62:65], v[184:187], v[90:93]
	v_mfma_f32_16x16x32_bf16 v[142:145], v[54:57], v[160:163], v[142:145]
	v_mfma_f32_16x16x32_bf16 v[138:141], v[152:155], v[160:163], v[138:141]
	v_mfma_f32_16x16x32_bf16 v[126:129], v[54:57], v[168:171], v[126:129]
	v_mfma_f32_16x16x32_bf16 v[122:125], v[152:155], v[168:171], v[122:125]
	v_mfma_f32_16x16x32_bf16 v[110:113], v[54:57], v[176:179], v[110:113]
	v_mfma_f32_16x16x32_bf16 v[106:109], v[152:155], v[176:179], v[106:109]
	v_mfma_f32_16x16x32_bf16 v[94:97], v[54:57], v[188:191], v[94:97]
	v_mfma_f32_16x16x32_bf16 v[90:93], v[152:155], v[188:191], v[90:93]
	s_setprio 0
.Lg9_skip_0:
	s_barrier
	s_add_i32 s44, 0, 0x14000
	s_add_i32 s42, s42, s18
	v_add_u32_e32 v36, s44, v150
	v_lshl_add_u64 v[146:147], s[10:11], 0, v[0:1]
	s_mov_b32 m0, s42
	ds_read_b128 v[202:205], v36
	ds_read_b128 v[206:209], v36 offset:1024
	ds_read_b128 v[210:213], v36 offset:2048
	ds_read_b128 v[214:217], v36 offset:3072
	global_load_lds_dwordx4 v[146:147], off
	v_lshl_add_u64 v[180:181], s[10:11], 0, v[34:35]
	s_add_i32 m0, s42, 0x2000
	s_nop 0
	global_load_lds_dwordx4 v[180:181], off
	s_barrier
	s_waitcnt lgkmcnt(0)
	s_cmp_eq_u32 s32, 2
	s_cbranch_scc1 .Lg9_skip_1
	s_setprio 1
	s_waitcnt lgkmcnt(0)
	v_mfma_f32_16x16x32_bf16 v[134:137], v[202:205], v[156:159], v[134:137]
	v_mfma_f32_16x16x32_bf16 v[130:133], v[210:213], v[156:159], v[130:133]
	v_mfma_f32_16x16x32_bf16 v[118:121], v[202:205], v[164:167], v[118:121]
	v_mfma_f32_16x16x32_bf16 v[114:117], v[210:213], v[164:167], v[114:117]
	v_mfma_f32_16x16x32_bf16 v[102:105], v[202:205], v[172:175], v[102:105]
	v_mfma_f32_16x16x32_bf16 v[98:101], v[210:213], v[172:175], v[98:101]
	v_mfma_f32_16x16x32_bf16 v[86:89], v[202:205], v[184:187], v[86:89]
	v_mfma_f32_16x16x32_bf16 v[82:85], v[210:213], v[184:187], v[82:85]
	v_mfma_f32_16x16x32_bf16 v[134:137], v[206:209], v[160:163], v[134:137]
	v_mfma_f32_16x16x32_bf16 v[130:133], v[214:217], v[160:163], v[130:133]
	v_mfma_f32_16x16x32_bf16 v[118:121], v[206:209], v[168:171], v[118:121]
	v_mfma_f32_16x16x32_bf16 v[114:117], v[214:217], v[168:171], v[114:117]
	v_mfma_f32_16x16x32_bf16 v[102:105], v[206:209], v[176:179], v[102:105]
	v_mfma_f32_16x16x32_bf16 v[98:101], v[214:217], v[176:179], v[98:101]
	v_mfma_f32_16x16x32_bf16 v[86:89], v[206:209], v[188:191], v[86:89]
	v_mfma_f32_16x16x32_bf16 v[82:85], v[214:217], v[188:191], v[82:85]
	s_setprio 0
.Lg9_skip_1:
	s_mov_b32 m0, s24
	v_lshl_add_u64 v[182:183], s[12:13], 0, v[0:1]
	s_barrier
	ds_read_b128 v[156:159], v151 offset:16384
	ds_read_b128 v[160:163], v151 offset:17408
	ds_read_b128 v[164:167], v151 offset:18432
	ds_read_b128 v[168:171], v151 offset:19456
	ds_read_b128 v[172:175], v151 offset:20480
	ds_read_b128 v[176:179], v151 offset:21504
	ds_read_b128 v[184:187], v151 offset:22528
	ds_read_b128 v[188:191], v151 offset:23552
	global_load_lds_dwordx4 v[182:183], off
	v_lshl_add_u64 v[194:195], s[12:13], 0, v[34:35]
	s_mov_b32 m0, s25
	s_nop 0
	global_load_lds_dwordx4 v[194:195], off
	s_barrier
	s_waitcnt lgkmcnt(0)
	s_cmp_eq_u32 s32, 1
	s_cbranch_scc1 .Lg9_skip_2
	s_setprio 1
	s_waitcnt lgkmcnt(0)
	v_mfma_f32_16x16x32_bf16 v[78:81], v[46:49], v[156:159], v[78:81]
	v_mfma_f32_16x16x32_bf16 v[74:77], v[62:65], v[156:159], v[74:77]
	v_mfma_f32_16x16x32_bf16 v[58:61], v[46:49], v[164:167], v[58:61]
	v_mfma_f32_16x16x32_bf16 v[50:53], v[62:65], v[164:167], v[50:53]
	v_mfma_f32_16x16x32_bf16 v[30:33], v[46:49], v[172:175], v[30:33]
	v_mfma_f32_16x16x32_bf16 v[26:29], v[62:65], v[172:175], v[26:29]
	v_mfma_f32_16x16x32_bf16 v[14:17], v[46:49], v[184:187], v[14:17]
	v_mfma_f32_16x16x32_bf16 v[10:13], v[62:65], v[184:187], v[10:13]
	v_mfma_f32_16x16x32_bf16 v[78:81], v[54:57], v[160:163], v[78:81]
	v_mfma_f32_16x16x32_bf16 v[74:77], v[152:155], v[160:163], v[74:77]
	v_mfma_f32_16x16x32_bf16 v[58:61], v[54:57], v[168:171], v[58:61]
	v_mfma_f32_16x16x32_bf16 v[50:53], v[152:155], v[168:171], v[50:53]
	v_mfma_f32_16x16x32_bf16 v[30:33], v[54:57], v[176:179], v[30:33]
	v_mfma_f32_16x16x32_bf16 v[26:29], v[152:155], v[176:179], v[26:29]
	v_mfma_f32_16x16x32_bf16 v[14:17], v[54:57], v[188:191], v[14:17]
	v_mfma_f32_16x16x32_bf16 v[10:13], v[152:155], v[188:191], v[10:13]
	s_setprio 0
; #define PG8_STAGE(bufoff, gbase, voff) do { _Pragma("unroll") for (int _i = 0; _i < 2; ++_i) \
;         __builtin_amdgcn_global_load_lds((const unsigned*)((const char*)(gbase) + (voff)[_i]), (LAS unsigned*)(lds + (bufoff) + ldsw + _i * 8192), 16, 0, 0); } while (0)
; #define PG8_LDA(dst, b, h) do { _Pragma("unroll") for (int m = 0; m < 4; ++m) _Pragma("unroll") for (int k = 0; k < 2; ++k) dst[m][k] = *(const LAS bf16x8*)(lds + PG8_SA(b, h) + aoff + m * 2048 + k * 1024); } while (0)
; #define PG8_LDB(dst, b, h) do { _Pragma("unroll") for (int n = 0; n < 2; ++n) _Pragma("unroll") for (int k = 0; k < 2; ++k) dst[n][k] = *(const LAS bf16x8*)(lds + PG8_SB(b, h) + boff + n * 2048 + k * 1024); } while (0)
; #define PG8_MMA(ai, bj, At, Bt) do { __builtin_amdgcn_s_setprio(1); _Pragma("unroll") for (int m = 0; m < 4; ++m) _Pragma("unroll") for (int n = 0; n < 2; ++n) _Pragma("unroll") for (int k = 0; k < 2; ++k) \
;         acc[ai][bj][m][n] = __builtin_amdgcn_mfma_f32_16x16x32_bf16(Bt[n][k], At[m][k], acc[ai][bj][m][n], 0, 0, 0); __builtin_amdgcn_s_setprio(0); } while (0)
; #define PG8_WAIT_V(n) asm volatile("s_waitcnt vmcnt(" #n ")" ::: "memory")
; #define PG8_WAIT_L(n) asm volatile("s_waitcnt lgkmcnt(" #n ")" ::: "memory")
; #define PG8_BAR __builtin_amdgcn_s_barrier()
; #define PG8_SCHED __builtin_amdgcn_sched_barrier(0)
; template <class Epi, class SchedT>
; DI void gemm_phase(LAS unsigned char* lds, const Gemm g, const SchedT& S, const Epi& E) {
;     ...
;             PG8_STAGE(PG8_SB(0, 1), b2 + hstepB, voffB);
;             PG8_WAIT_V(6); PG8_BAR; PG8_MMA(1, 1, At, B1); PG8_BAR;
;             PG8_LDB(B0, 1, 0); PG8_SCHED; PG8_LDA(At, 1, 0); PG8_STAGE(PG8_SA(0, 1), a2 + hstepA, voffA);
;             PG8_WAIT_L(8); PG8_BAR; PG8_WAIT_L(0); PG8_MMA(0, 0, At, B0); PG8_BAR; PG8_SCHED;
;             PG8_LDB(B1, 1, 1); PG8_STAGE(PG8_SB(1, 0), b3, voffB);
;             PG8_BAR; PG8_WAIT_L(0); PG8_MMA(0, 1, At, B1); PG8_BAR;
.Lg9_skip_2:
	s_barrier
	s_add_u32 s42, s10, 0x160000
	s_addc_u32 s43, s11, 0
	s_add_i32 s44, s44, s18
	v_lshl_add_u64 v[36:37], s[42:43], 0, v[0:1]
	s_mov_b32 m0, s44
	s_nop 0
	global_load_lds_dwordx4 v[36:37], off
	v_lshl_add_u64 v[36:37], s[42:43], 0, v[34:35]
	s_add_i32 m0, s44, 0x2000
	s_nop 0
	global_load_lds_dwordx4 v[36:37], off
	s_waitcnt vmcnt(6)
	s_barrier
	s_cmp_eq_u32 s32, 1
	s_cbranch_scc1 .Lg9_skip_3
	s_setprio 1
	v_mfma_f32_16x16x32_bf16 v[42:45], v[202:205], v[164:167], v[42:45]
	v_mfma_f32_16x16x32_bf16 v[36:39], v[210:213], v[164:167], v[38:41]
	v_mfma_f32_16x16x32_bf16 v[22:25], v[202:205], v[172:175], v[22:25]
	v_mfma_f32_16x16x32_bf16 v[18:21], v[210:213], v[172:175], v[18:21]
	v_mfma_f32_16x16x32_bf16 v[6:9], v[202:205], v[184:187], v[6:9]
	v_mfma_f32_16x16x32_bf16 v[2:5], v[210:213], v[184:187], v[2:5]
	v_mfma_f32_16x16x32_bf16 v[46:49], v[202:205], v[156:159], v[70:73]
	v_mfma_f32_16x16x32_bf16 v[54:57], v[210:213], v[156:159], v[66:69]
	v_mfma_f32_16x16x32_bf16 v[42:45], v[206:209], v[168:171], v[42:45]
	v_mfma_f32_16x16x32_bf16 v[36:39], v[214:217], v[168:171], v[36:39]
	v_mfma_f32_16x16x32_bf16 v[22:25], v[206:209], v[176:179], v[22:25]
	v_mfma_f32_16x16x32_bf16 v[18:21], v[214:217], v[176:179], v[18:21]
	v_mfma_f32_16x16x32_bf16 v[6:9], v[206:209], v[188:191], v[6:9]
	v_mfma_f32_16x16x32_bf16 v[2:5], v[214:217], v[188:191], v[2:5]
	v_mfma_f32_16x16x32_bf16 v[46:49], v[206:209], v[160:163], v[46:49]
	v_mfma_f32_16x16x32_bf16 v[54:57], v[214:217], v[160:163], v[54:57]
	s_setprio 0
.Lg9_skip_3:
	s_add_i32 s42, 0, 0x18000
	v_add_u32_e32 v40, s42, v150
	s_barrier
	ds_read_b128 v[62:65], v40
	ds_read_b128 v[66:69], v40 offset:1024
	ds_read_b128 v[70:73], v40 offset:2048
	ds_read_b128 v[152:155], v40 offset:3072
	s_add_u32 s12, s12, 0x160000
	s_addc_u32 s13, s13, 0
	s_mov_b32 m0, s26
	v_lshl_add_u64 v[40:41], s[12:13], 0, v[0:1]
	ds_read_b128 v[156:159], v151 offset:32768
	ds_read_b128 v[160:163], v151 offset:33792
	ds_read_b128 v[164:167], v151 offset:34816
	ds_read_b128 v[168:171], v151 offset:35840
	ds_read_b128 v[172:175], v151 offset:36864
	ds_read_b128 v[176:179], v151 offset:37888
	ds_read_b128 v[184:187], v151 offset:38912
	ds_read_b128 v[188:191], v151 offset:39936
	global_load_lds_dwordx4 v[40:41], off
	v_lshl_add_u64 v[40:41], s[12:13], 0, v[34:35]
	s_mov_b32 m0, s27
	s_nop 0
	global_load_lds_dwordx4 v[40:41], off
	s_waitcnt lgkmcnt(8)
	s_barrier
	s_waitcnt lgkmcnt(0)
	s_cmp_eq_u32 s32, 2
	s_cbranch_scc1 .Lg9_skip_4
	s_setprio 1
	s_waitcnt lgkmcnt(0)
	v_mfma_f32_16x16x32_bf16 v[142:145], v[62:65], v[156:159], v[142:145]
	v_mfma_f32_16x16x32_bf16 v[138:141], v[70:73], v[156:159], v[138:141]
	v_mfma_f32_16x16x32_bf16 v[126:129], v[62:65], v[164:167], v[126:129]
	v_mfma_f32_16x16x32_bf16 v[122:125], v[70:73], v[164:167], v[122:125]
	v_mfma_f32_16x16x32_bf16 v[110:113], v[62:65], v[172:175], v[110:113]
	v_mfma_f32_16x16x32_bf16 v[106:109], v[70:73], v[172:175], v[106:109]
	v_mfma_f32_16x16x32_bf16 v[94:97], v[62:65], v[184:187], v[94:97]
	v_mfma_f32_16x16x32_bf16 v[90:93], v[70:73], v[184:187], v[90:93]
	v_mfma_f32_16x16x32_bf16 v[142:145], v[66:69], v[160:163], v[142:145]
	v_mfma_f32_16x16x32_bf16 v[138:141], v[152:155], v[160:163], v[138:141]
	v_mfma_f32_16x16x32_bf16 v[126:129], v[66:69], v[168:171], v[126:129]
	v_mfma_f32_16x16x32_bf16 v[122:125], v[152:155], v[168:171], v[122:125]
	v_mfma_f32_16x16x32_bf16 v[110:113], v[66:69], v[176:179], v[110:113]
	v_mfma_f32_16x16x32_bf16 v[106:109], v[152:155], v[176:179], v[106:109]
	v_mfma_f32_16x16x32_bf16 v[94:97], v[66:69], v[188:191], v[94:97]
	v_mfma_f32_16x16x32_bf16 v[90:93], v[152:155], v[188:191], v[90:93]
	s_setprio 0
.Lg9_skip_4:
	s_barrier
	s_add_i32 s12, 0, 0x1c000
	v_add_u32_e32 v40, s12, v150
	s_add_i32 s13, s42, s18
	ds_read_b128 v[202:205], v40
	ds_read_b128 v[206:209], v40 offset:1024
	ds_read_b128 v[210:213], v40 offset:2048
	ds_read_b128 v[214:217], v40 offset:3072
	v_lshl_add_u64 v[40:41], v[146:147], 0, s[90:91]
	s_mov_b32 m0, s13
	s_nop 0
	global_load_lds_dwordx4 v[40:41], off
	v_lshl_add_u64 v[40:41], v[180:181], 0, s[90:91]
	s_add_i32 m0, s13, 0x2000
	s_nop 0
	global_load_lds_dwordx4 v[40:41], off
	s_barrier
	s_waitcnt lgkmcnt(0)
	s_cmp_eq_u32 s32, 2
	s_cbranch_scc1 .Lg9_skip_5
	s_setprio 1
	s_waitcnt lgkmcnt(0)
	v_mfma_f32_16x16x32_bf16 v[134:137], v[202:205], v[156:159], v[134:137]
	v_mfma_f32_16x16x32_bf16 v[130:133], v[210:213], v[156:159], v[130:133]
	v_mfma_f32_16x16x32_bf16 v[118:121], v[202:205], v[164:167], v[118:121]
	v_mfma_f32_16x16x32_bf16 v[114:117], v[210:213], v[164:167], v[114:117]
	v_mfma_f32_16x16x32_bf16 v[102:105], v[202:205], v[172:175], v[102:105]
	v_mfma_f32_16x16x32_bf16 v[98:101], v[210:213], v[172:175], v[98:101]
	v_mfma_f32_16x16x32_bf16 v[86:89], v[202:205], v[184:187], v[86:89]
	v_mfma_f32_16x16x32_bf16 v[82:85], v[210:213], v[184:187], v[82:85]
	v_mfma_f32_16x16x32_bf16 v[134:137], v[206:209], v[160:163], v[134:137]
	v_mfma_f32_16x16x32_bf16 v[130:133], v[214:217], v[160:163], v[130:133]
	v_mfma_f32_16x16x32_bf16 v[118:121], v[206:209], v[168:171], v[118:121]
	v_mfma_f32_16x16x32_bf16 v[114:117], v[214:217], v[168:171], v[114:117]
	v_mfma_f32_16x16x32_bf16 v[102:105], v[206:209], v[176:179], v[102:105]
	v_mfma_f32_16x16x32_bf16 v[98:101], v[214:217], v[176:179], v[98:101]
	v_mfma_f32_16x16x32_bf16 v[86:89], v[206:209], v[188:191], v[86:89]
	v_mfma_f32_16x16x32_bf16 v[82:85], v[214:217], v[188:191], v[82:85]
	s_setprio 0
; #define PG8_STAGE(bufoff, gbase, voff) do { _Pragma("unroll") for (int _i = 0; _i < 2; ++_i) \
;         __builtin_amdgcn_global_load_lds((const unsigned*)((const char*)(gbase) + (voff)[_i]), (LAS unsigned*)(lds + (bufoff) + ldsw + _i * 8192), 16, 0, 0); } while (0)
; #define PG8_LDA(dst, b, h) do { _Pragma("unroll") for (int m = 0; m < 4; ++m) _Pragma("unroll") for (int k = 0; k < 2; ++k) dst[m][k] = *(const LAS bf16x8*)(lds + PG8_SA(b, h) + aoff + m * 2048 + k * 1024); } while (0)
; #define PG8_MMA(ai, bj, At, Bt) do { __builtin_amdgcn_s_setprio(1); _Pragma("unroll") for (int m = 0; m < 4; ++m) _Pragma("unroll") for (int n = 0; n < 2; ++n) _Pragma("unroll") for (int k = 0; k < 2; ++k) \
;         acc[ai][bj][m][n] = __builtin_amdgcn_mfma_f32_16x16x32_bf16(Bt[n][k], At[m][k], acc[ai][bj][m][n], 0, 0, 0); __builtin_amdgcn_s_setprio(0); } while (0)
; #define PG8_WAIT_V(n) asm volatile("s_waitcnt vmcnt(" #n ")" ::: "memory")
; #define PG8_WAIT_L(n) asm volatile("s_waitcnt lgkmcnt(" #n ")" ::: "memory")
; #define PG8_BAR __builtin_amdgcn_s_barrier()
; #define PG8_SCHED __builtin_amdgcn_sched_barrier(0)
; template <class Epi, class SchedT>
; DI void gemm_phase(LAS unsigned char* lds, const Gemm g, const SchedT& S, const Epi& E) {
;     ...
;             PG8_LDA(At, 1, 1); PG8_STAGE(PG8_SA(1, 0), a3, voffA);
;             PG8_BAR; PG8_WAIT_L(0); PG8_MMA(1, 0, At, B0); PG8_BAR; PG8_SCHED;
;             PG8_STAGE(PG8_SB(1, 1), b3 + hstepB, voffB);
;             PG8_WAIT_V(6); PG8_BAR; PG8_MMA(1, 1, At, B1); PG8_BAR;
;     DI void operator()(AccRef acc, const Unit& u, int wr, int wc, int fr, int fq) const {
;         const int row0 = u.pm * 256; const int midx = row0 < ML ? (row0 >> 12) : 4;
;         const float* src = row0 < ML ? xl : (xc - (size_t)ML * D);
;         const float* gp = gate + (size_t)midx * 12288;
;         const int col0 = u.pn * 256 + wc * 32 + 4 * fq;
;         f32x4 gv[2][2];
; #pragma unroll
;         for (int bj = 0; bj < 2; ++bj)
; #pragma unroll
;             for (int n = 0; n < 2; ++n) gv[bj][n] = *(const f32x4*)(gp + col0 + bj * 128 + n * 16);
.Lg9_skip_5:
	s_mov_b32 m0, s31
	v_lshl_add_u64 v[40:41], v[182:183], 0, s[90:91]
	s_barrier
	ds_read_b128 v[156:159], v151 offset:49152
	ds_read_b128 v[160:163], v151 offset:50176
	ds_read_b128 v[164:167], v151 offset:51200
	ds_read_b128 v[168:171], v151 offset:52224
	ds_read_b128 v[172:175], v151 offset:53248
	ds_read_b128 v[176:179], v151 offset:54272
	ds_read_b128 v[184:187], v151 offset:55296
	ds_read_b128 v[188:191], v151 offset:56320
	global_load_lds_dwordx4 v[40:41], off
	v_lshl_add_u64 v[40:41], v[194:195], 0, s[90:91]
	s_mov_b32 m0, s34
	s_nop 0
	global_load_lds_dwordx4 v[40:41], off
	s_barrier
	s_waitcnt lgkmcnt(0)
	s_cmp_eq_u32 s32, 1
	s_cbranch_scc1 .Lg9_skip_6
	s_setprio 1
	s_waitcnt lgkmcnt(0)
	v_mfma_f32_16x16x32_bf16 v[78:81], v[62:65], v[156:159], v[78:81]
	v_mfma_f32_16x16x32_bf16 v[74:77], v[70:73], v[156:159], v[74:77]
	v_mfma_f32_16x16x32_bf16 v[58:61], v[62:65], v[164:167], v[58:61]
	v_mfma_f32_16x16x32_bf16 v[50:53], v[70:73], v[164:167], v[50:53]
	v_mfma_f32_16x16x32_bf16 v[30:33], v[62:65], v[172:175], v[30:33]
	v_mfma_f32_16x16x32_bf16 v[26:29], v[70:73], v[172:175], v[26:29]
	v_mfma_f32_16x16x32_bf16 v[14:17], v[62:65], v[184:187], v[14:17]
	v_mfma_f32_16x16x32_bf16 v[10:13], v[70:73], v[184:187], v[10:13]
	v_mfma_f32_16x16x32_bf16 v[78:81], v[66:69], v[160:163], v[78:81]
	v_mfma_f32_16x16x32_bf16 v[74:77], v[152:155], v[160:163], v[74:77]
	v_mfma_f32_16x16x32_bf16 v[58:61], v[66:69], v[168:171], v[58:61]
	v_mfma_f32_16x16x32_bf16 v[50:53], v[152:155], v[168:171], v[50:53]
	v_mfma_f32_16x16x32_bf16 v[30:33], v[66:69], v[176:179], v[30:33]
	v_mfma_f32_16x16x32_bf16 v[26:29], v[152:155], v[176:179], v[26:29]
	v_mfma_f32_16x16x32_bf16 v[14:17], v[66:69], v[188:191], v[14:17]
	v_mfma_f32_16x16x32_bf16 v[10:13], v[152:155], v[188:191], v[10:13]
	s_setprio 0
.Lg9_skip_6:
	s_barrier
	s_add_u32 s10, s10, 0x160080
	s_addc_u32 s11, s11, 0
	s_add_i32 s12, s12, s18
	v_lshl_add_u64 v[40:41], s[10:11], 0, v[0:1]
	s_mov_b32 m0, s12
	s_nop 0
	global_load_lds_dwordx4 v[40:41], off
	v_lshl_add_u64 v[40:41], s[10:11], 0, v[34:35]
	s_add_i32 m0, s12, 0x2000
	s_nop 0
	global_load_lds_dwordx4 v[40:41], off
	s_waitcnt vmcnt(6)
	s_barrier
	s_cmp_eq_u32 s32, 1
	s_cbranch_scc1 .Lg9_skip_7
	s_setprio 1
	v_mfma_f32_16x16x32_bf16 v[46:49], v[202:205], v[156:159], v[46:49]
	v_mfma_f32_16x16x32_bf16 v[70:73], v[206:209], v[160:163], v[46:49]
	v_mfma_f32_16x16x32_bf16 v[46:49], v[210:213], v[156:159], v[54:57]
	v_mfma_f32_16x16x32_bf16 v[40:43], v[202:205], v[164:167], v[42:45]
	v_mfma_f32_16x16x32_bf16 v[36:39], v[210:213], v[164:167], v[36:39]
	v_mfma_f32_16x16x32_bf16 v[22:25], v[202:205], v[172:175], v[22:25]
	v_mfma_f32_16x16x32_bf16 v[18:21], v[210:213], v[172:175], v[18:21]
	v_mfma_f32_16x16x32_bf16 v[6:9], v[202:205], v[184:187], v[6:9]
	v_mfma_f32_16x16x32_bf16 v[2:5], v[210:213], v[184:187], v[2:5]
	v_mfma_f32_16x16x32_bf16 v[66:69], v[214:217], v[160:163], v[46:49]
	v_mfma_f32_16x16x32_bf16 v[42:45], v[206:209], v[168:171], v[40:43]
	v_mfma_f32_16x16x32_bf16 v[38:41], v[214:217], v[168:171], v[36:39]
	v_mfma_f32_16x16x32_bf16 v[22:25], v[206:209], v[176:179], v[22:25]
	v_mfma_f32_16x16x32_bf16 v[18:21], v[214:217], v[176:179], v[18:21]
	v_mfma_f32_16x16x32_bf16 v[6:9], v[206:209], v[188:191], v[6:9]
	v_mfma_f32_16x16x32_bf16 v[2:5], v[214:217], v[188:191], v[2:5]
	s_setprio 0
.Lg9_skip_7:
	s_add_i32 s41, s41, 2
	s_add_u32 s8, s8, 0x100
	s_addc_u32 s9, s9, 0
	s_add_u32 s39, s39, 0x100
	s_addc_u32 s40, s40, 0
	s_cmpk_gt_u32 s41, 0x55
	s_barrier
	s_cbranch_scc0 .LBB0_1705
	s_min_i32 s8, s38, 64
	s_ashr_i32 s8, s8, 4
	v_mov_b32_e32 v0, v149
	s_mov_b32 s10, s30
	v_mov_b32_e32 v152, v148
	s_mov_b32 s11, s17
	s_lshl_b32 s12, s38, 8
	s_mul_hi_i32 s9, s8, 0xc000
	s_mul_i32 s8, s8, 0xc000
	s_add_u32 s8, s28, s8
	s_addc_u32 s9, s29, s9
	s_lshl_b32 s13, s33, 8
	s_lshl_b32 s10, s10, 5
	s_add_i32 s10, s10, s13
	v_lshl_add_u32 v146, v0, 2, s10
	v_ashrrev_i32_e32 v147, 31, v146
	v_lshl_add_u64 v[34:35], v[146:147], 2, s[8:9]
	s_lshl_b32 s8, s11, 6
	s_add_i32 s8, s8, s12
	v_add_u32_e32 v152, s8, v152
	v_ashrrev_i32_e32 v153, 31, v152
	v_lshlrev_b64 v[152:153], 12, v[152:153]
	v_lshl_add_u64 v[152:153], s[4:5], 0, v[152:153]
	v_lshl_add_u64 v[146:147], v[146:147], 1, v[152:153]
	global_load_dwordx4 v[62:65], v[34:35], off
	global_load_dwordx4 v[54:57], v[34:35], off offset:64
	global_load_dwordx4 v[46:49], v[34:35], off offset:512
	s_nop 0
	global_load_dwordx4 v[34:37], v[34:35], off offset:576
	s_mov_b64 s[8:9], 0x10000
	s_cmp_eq_u32 s32, 2
	s_cbranch_scc0 .Lg9_e_full0
	s_mov_b64 s[8:9], 0x80000
	s_branch .Lg9_e_grp5
; DI unsigned pk2(float a, float b) { f32x2 v = {a, b}; bfv2 r = __builtin_convertvector(v, bfv2); return __builtin_bit_cast(unsigned, r); }
;     DI void operator()(AccRef acc, const Unit& u, int wr, int wc, int fr, int fq) const {
;     ...
;         if (xb) {
; #pragma unroll
;             for (int ai = 0; ai < 2; ++ai)
; #pragma unroll
;                 for (int m = 0; m < 4; ++m) { const size_t off = (size_t)(row0 + wr * 64 + fr + ai * 128 + m * 16) * D + col0;
; #pragma unroll
;                     for (int bj = 0; bj < 2; ++bj)
; #pragma unroll
;                         for (int n = 0; n < 2; ++n) { const size_t o2 = off + bj * 128 + n * 16;
;                             const f32x4 r = bf4(*(const u32x2*)(xb + o2)) + gv[bj][n] * acc[ai][bj][m][n];
;                             u32x2 w; w.x = pk2(r[0], r[1]); w.y = pk2(r[2], r[3]); *(u32x2*)(out + o2) = w; }
;                     asm volatile("" ::: "memory"); }
.Lg9_e_full0:
	global_load_dwordx2 v[152:153], v[146:147], off
	global_load_dwordx2 v[206:207], v[146:147], off offset:32
	global_load_dwordx2 v[208:209], v[146:147], off offset:256
	global_load_dwordx2 v[210:211], v[146:147], off offset:288
	s_waitcnt vmcnt(3)
	v_lshlrev_b32_e32 v154, 16, v152
	v_and_b32_e32 v155, 0xffff0000, v152
	v_lshlrev_b32_e32 v152, 16, v153
	v_and_b32_e32 v153, 0xffff0000, v153
	v_pk_fma_f32 v[144:145], v[144:145], v[64:65], v[152:153]
	v_pk_fma_f32 v[142:143], v[142:143], v[62:63], v[154:155]
	s_nop 0
	v_cvt_pk_bf16_f32 v142, v142, v143
	v_cvt_pk_bf16_f32 v143, v144, v145
	global_store_dwordx2 v[146:147], v[142:143], off
	s_waitcnt vmcnt(3)
	v_lshlrev_b32_e32 v144, 16, v206
	v_and_b32_e32 v145, 0xffff0000, v206
	v_lshlrev_b32_e32 v142, 16, v207
	v_and_b32_e32 v143, 0xffff0000, v207
	v_pk_fma_f32 v[140:141], v[140:141], v[56:57], v[142:143]
	v_pk_fma_f32 v[138:139], v[138:139], v[54:55], v[144:145]
	s_nop 0
	v_cvt_pk_bf16_f32 v138, v138, v139
	v_cvt_pk_bf16_f32 v139, v140, v141
	global_store_dwordx2 v[146:147], v[138:139], off offset:32
	s_waitcnt vmcnt(3)
	v_lshlrev_b32_e32 v140, 16, v208
	v_and_b32_e32 v141, 0xffff0000, v208
	v_lshlrev_b32_e32 v138, 16, v209
	v_and_b32_e32 v139, 0xffff0000, v209
	v_pk_fma_f32 v[136:137], v[136:137], v[48:49], v[138:139]
	v_pk_fma_f32 v[134:135], v[134:135], v[46:47], v[140:141]
	s_nop 0
	v_cvt_pk_bf16_f32 v134, v134, v135
	v_cvt_pk_bf16_f32 v135, v136, v137
	global_store_dwordx2 v[146:147], v[134:135], off offset:256
	s_waitcnt vmcnt(3)
	v_lshlrev_b32_e32 v136, 16, v210
	v_and_b32_e32 v137, 0xffff0000, v210
	v_lshlrev_b32_e32 v134, 16, v211
	v_and_b32_e32 v135, 0xffff0000, v211
	v_pk_fma_f32 v[132:133], v[132:133], v[36:37], v[134:135]
	v_pk_fma_f32 v[130:131], v[130:131], v[34:35], v[136:137]
	s_nop 0
	v_cvt_pk_bf16_f32 v130, v130, v131
	v_cvt_pk_bf16_f32 v131, v132, v133
	global_store_dwordx2 v[146:147], v[130:131], off offset:288
	v_lshl_add_u64 v[130:131], v[146:147], 0, s[8:9]
	s_mov_b32 s8, 0x10000
	v_add_co_u32_e32 v132, vcc, s8, v146
	s_mov_b64 s[8:9], 0x20000
	s_nop 0
	v_addc_co_u32_e32 v133, vcc, 0, v147, vcc
	global_load_dwordx2 v[134:135], v[132:133], off
	global_load_dwordx2 v[206:207], v[130:131], off offset:32
	global_load_dwordx2 v[208:209], v[130:131], off offset:256
	global_load_dwordx2 v[210:211], v[130:131], off offset:288
	s_waitcnt vmcnt(3)
	v_lshlrev_b32_e32 v136, 16, v134
	v_and_b32_e32 v137, 0xffff0000, v134
	v_lshlrev_b32_e32 v134, 16, v135
	v_and_b32_e32 v135, 0xffff0000, v135
	v_pk_fma_f32 v[128:129], v[128:129], v[64:65], v[134:135]
	v_pk_fma_f32 v[126:127], v[126:127], v[62:63], v[136:137]
	s_nop 0
	v_cvt_pk_bf16_f32 v126, v126, v127
	v_cvt_pk_bf16_f32 v127, v128, v129
	global_store_dwordx2 v[132:133], v[126:127], off
	s_waitcnt vmcnt(3)
	v_lshlrev_b32_e32 v128, 16, v206
	v_and_b32_e32 v129, 0xffff0000, v206
	v_lshlrev_b32_e32 v126, 16, v207
	v_and_b32_e32 v127, 0xffff0000, v207
	v_pk_fma_f32 v[124:125], v[124:125], v[56:57], v[126:127]
	v_pk_fma_f32 v[122:123], v[122:123], v[54:55], v[128:129]
	s_nop 0
	v_cvt_pk_bf16_f32 v122, v122, v123
	v_cvt_pk_bf16_f32 v123, v124, v125
	global_store_dwordx2 v[130:131], v[122:123], off offset:32
	s_waitcnt vmcnt(3)
	v_lshlrev_b32_e32 v124, 16, v208
	v_and_b32_e32 v125, 0xffff0000, v208
	v_lshlrev_b32_e32 v122, 16, v209
	v_and_b32_e32 v123, 0xffff0000, v209
	v_pk_fma_f32 v[120:121], v[120:121], v[48:49], v[122:123]
	v_pk_fma_f32 v[118:119], v[118:119], v[46:47], v[124:125]
	s_nop 0
	v_cvt_pk_bf16_f32 v118, v118, v119
	v_cvt_pk_bf16_f32 v119, v120, v121
	global_store_dwordx2 v[130:131], v[118:119], off offset:256
	s_waitcnt vmcnt(3)
	v_lshlrev_b32_e32 v120, 16, v210
	v_and_b32_e32 v121, 0xffff0000, v210
	v_lshlrev_b32_e32 v118, 16, v211
	v_and_b32_e32 v119, 0xffff0000, v211
	v_pk_fma_f32 v[116:117], v[116:117], v[36:37], v[118:119]
	v_pk_fma_f32 v[114:115], v[114:115], v[34:35], v[120:121]
	s_nop 0
	v_cvt_pk_bf16_f32 v114, v114, v115
	v_cvt_pk_bf16_f32 v115, v116, v117
	global_store_dwordx2 v[130:131], v[114:115], off offset:288
	v_lshl_add_u64 v[114:115], v[146:147], 0, s[8:9]
	s_mov_b32 s8, 0x20000
	v_add_co_u32_e32 v116, vcc, s8, v146
	s_mov_b64 s[8:9], 0x30000
	s_nop 0
	v_addc_co_u32_e32 v117, vcc, 0, v147, vcc
	global_load_dwordx2 v[118:119], v[116:117], off
	global_load_dwordx2 v[206:207], v[114:115], off offset:32
	global_load_dwordx2 v[208:209], v[114:115], off offset:256
	global_load_dwordx2 v[210:211], v[114:115], off offset:288
	s_waitcnt vmcnt(3)
	v_lshlrev_b32_e32 v120, 16, v118
	v_and_b32_e32 v121, 0xffff0000, v118
	v_lshlrev_b32_e32 v118, 16, v119
	v_and_b32_e32 v119, 0xffff0000, v119
	v_pk_fma_f32 v[112:113], v[112:113], v[64:65], v[118:119]
	v_pk_fma_f32 v[110:111], v[110:111], v[62:63], v[120:121]
	s_nop 0
	v_cvt_pk_bf16_f32 v110, v110, v111
	v_cvt_pk_bf16_f32 v111, v112, v113
	global_store_dwordx2 v[116:117], v[110:111], off
	s_waitcnt vmcnt(3)
	v_lshlrev_b32_e32 v112, 16, v206
	v_and_b32_e32 v113, 0xffff0000, v206
	v_lshlrev_b32_e32 v110, 16, v207
	v_and_b32_e32 v111, 0xffff0000, v207
	v_pk_fma_f32 v[108:109], v[108:109], v[56:57], v[110:111]
	v_pk_fma_f32 v[106:107], v[106:107], v[54:55], v[112:113]
	s_nop 0
	v_cvt_pk_bf16_f32 v106, v106, v107
	v_cvt_pk_bf16_f32 v107, v108, v109
	global_store_dwordx2 v[114:115], v[106:107], off offset:32
	s_waitcnt vmcnt(3)
	v_lshlrev_b32_e32 v108, 16, v208
	v_and_b32_e32 v109, 0xffff0000, v208
	v_lshlrev_b32_e32 v106, 16, v209
	v_and_b32_e32 v107, 0xffff0000, v209
	v_pk_fma_f32 v[104:105], v[104:105], v[48:49], v[106:107]
	v_pk_fma_f32 v[102:103], v[102:103], v[46:47], v[108:109]
	s_nop 0
	v_cvt_pk_bf16_f32 v102, v102, v103
	v_cvt_pk_bf16_f32 v103, v104, v105
	global_store_dwordx2 v[114:115], v[102:103], off offset:256
	s_waitcnt vmcnt(3)
; DI unsigned pk2(float a, float b) { f32x2 v = {a, b}; bfv2 r = __builtin_convertvector(v, bfv2); return __builtin_bit_cast(unsigned, r); }
;     DI void operator()(AccRef acc, const Unit& u, int wr, int wc, int fr, int fq) const {
;     ...
;         if (xb) {
; #pragma unroll
;             for (int ai = 0; ai < 2; ++ai)
; #pragma unroll
;                 for (int m = 0; m < 4; ++m) { const size_t off = (size_t)(row0 + wr * 64 + fr + ai * 128 + m * 16) * D + col0;
; #pragma unroll
;                     for (int bj = 0; bj < 2; ++bj)
; #pragma unroll
;                         for (int n = 0; n < 2; ++n) { const size_t o2 = off + bj * 128 + n * 16;
;                             const f32x4 r = bf4(*(const u32x2*)(xb + o2)) + gv[bj][n] * acc[ai][bj][m][n];
;                             u32x2 w; w.x = pk2(r[0], r[1]); w.y = pk2(r[2], r[3]); *(u32x2*)(out + o2) = w; }
;                     asm volatile("" ::: "memory"); }
	v_lshlrev_b32_e32 v104, 16, v210
	v_and_b32_e32 v105, 0xffff0000, v210
	v_lshlrev_b32_e32 v102, 16, v211
	v_and_b32_e32 v103, 0xffff0000, v211
	v_pk_fma_f32 v[100:101], v[100:101], v[36:37], v[102:103]
	v_pk_fma_f32 v[98:99], v[98:99], v[34:35], v[104:105]
	s_nop 0
	v_cvt_pk_bf16_f32 v98, v98, v99
	v_cvt_pk_bf16_f32 v99, v100, v101
	global_store_dwordx2 v[114:115], v[98:99], off offset:288
	v_lshl_add_u64 v[98:99], v[146:147], 0, s[8:9]
	s_mov_b32 s8, 0x30000
	v_add_co_u32_e32 v100, vcc, s8, v146
	s_mov_b64 s[8:9], 0x80000
	s_nop 0
	v_addc_co_u32_e32 v101, vcc, 0, v147, vcc
	global_load_dwordx2 v[102:103], v[100:101], off
	global_load_dwordx2 v[206:207], v[98:99], off offset:32
	global_load_dwordx2 v[208:209], v[98:99], off offset:256
	global_load_dwordx2 v[210:211], v[98:99], off offset:288
	s_waitcnt vmcnt(3)
	v_lshlrev_b32_e32 v104, 16, v102
	v_and_b32_e32 v105, 0xffff0000, v102
	v_lshlrev_b32_e32 v102, 16, v103
	v_and_b32_e32 v103, 0xffff0000, v103
	v_pk_fma_f32 v[96:97], v[96:97], v[64:65], v[102:103]
	v_pk_fma_f32 v[94:95], v[94:95], v[62:63], v[104:105]
	s_nop 0
	v_cvt_pk_bf16_f32 v94, v94, v95
	v_cvt_pk_bf16_f32 v95, v96, v97
	global_store_dwordx2 v[100:101], v[94:95], off
	s_waitcnt vmcnt(3)
	v_lshlrev_b32_e32 v96, 16, v206
	v_and_b32_e32 v97, 0xffff0000, v206
	v_lshlrev_b32_e32 v94, 16, v207
	v_and_b32_e32 v95, 0xffff0000, v207
	v_pk_fma_f32 v[92:93], v[92:93], v[56:57], v[94:95]
	v_pk_fma_f32 v[90:91], v[90:91], v[54:55], v[96:97]
	s_nop 0
	v_cvt_pk_bf16_f32 v90, v90, v91
	v_cvt_pk_bf16_f32 v91, v92, v93
	global_store_dwordx2 v[98:99], v[90:91], off offset:32
	s_waitcnt vmcnt(3)
	v_lshlrev_b32_e32 v92, 16, v208
	v_and_b32_e32 v93, 0xffff0000, v208
	v_lshlrev_b32_e32 v90, 16, v209
	v_and_b32_e32 v91, 0xffff0000, v209
	v_pk_fma_f32 v[88:89], v[88:89], v[48:49], v[90:91]
	v_pk_fma_f32 v[86:87], v[86:87], v[46:47], v[92:93]
	s_nop 0
	v_cvt_pk_bf16_f32 v86, v86, v87
	v_cvt_pk_bf16_f32 v87, v88, v89
	global_store_dwordx2 v[98:99], v[86:87], off offset:256
	s_waitcnt vmcnt(3)
	v_lshlrev_b32_e32 v88, 16, v210
	v_and_b32_e32 v89, 0xffff0000, v210
	v_lshlrev_b32_e32 v86, 16, v211
	v_and_b32_e32 v87, 0xffff0000, v211
	v_pk_fma_f32 v[84:85], v[84:85], v[36:37], v[86:87]
	v_pk_fma_f32 v[82:83], v[82:83], v[34:35], v[88:89]
	s_nop 0
	v_cvt_pk_bf16_f32 v82, v82, v83
	v_cvt_pk_bf16_f32 v83, v84, v85
	global_store_dwordx2 v[98:99], v[82:83], off offset:288
	s_cmp_eq_u32 s32, 1
	s_cbranch_scc0 .Lg9_e_grp5
	s_mov_b64 s[8:9], -1
	s_and_b64 vcc, exec, s[2:3]
	s_branch .Lg9_e_end
.Lg9_e_grp5:
	v_lshl_add_u64 v[82:83], v[146:147], 0, s[8:9]
	s_mov_b32 s8, 0x80000
	v_add_co_u32_e32 v84, vcc, s8, v146
	s_mov_b64 s[8:9], 0x90000
	s_nop 0
	v_addc_co_u32_e32 v85, vcc, 0, v147, vcc
	global_load_dwordx2 v[86:87], v[84:85], off
	global_load_dwordx2 v[206:207], v[82:83], off offset:32
	global_load_dwordx2 v[208:209], v[82:83], off offset:256
	global_load_dwordx2 v[210:211], v[82:83], off offset:288
	s_waitcnt vmcnt(3)
	v_lshlrev_b32_e32 v88, 16, v86
	v_and_b32_e32 v89, 0xffff0000, v86
	v_lshlrev_b32_e32 v86, 16, v87
	v_and_b32_e32 v87, 0xffff0000, v87
	v_pk_fma_f32 v[80:81], v[80:81], v[64:65], v[86:87]
	v_pk_fma_f32 v[78:79], v[78:79], v[62:63], v[88:89]
	s_nop 0
	v_cvt_pk_bf16_f32 v78, v78, v79
	v_cvt_pk_bf16_f32 v79, v80, v81
	global_store_dwordx2 v[84:85], v[78:79], off
	s_waitcnt vmcnt(3)
	v_lshlrev_b32_e32 v80, 16, v206
	v_and_b32_e32 v81, 0xffff0000, v206
	v_lshlrev_b32_e32 v78, 16, v207
	v_and_b32_e32 v79, 0xffff0000, v207
	v_pk_fma_f32 v[76:77], v[76:77], v[56:57], v[78:79]
	v_pk_fma_f32 v[74:75], v[74:75], v[54:55], v[80:81]
	s_nop 0
	v_cvt_pk_bf16_f32 v74, v74, v75
	v_cvt_pk_bf16_f32 v75, v76, v77
	global_store_dwordx2 v[82:83], v[74:75], off offset:32
	s_waitcnt vmcnt(3)
	v_lshlrev_b32_e32 v76, 16, v208
	v_and_b32_e32 v77, 0xffff0000, v208
	v_lshlrev_b32_e32 v74, 16, v209
	v_and_b32_e32 v75, 0xffff0000, v209
	v_pk_fma_f32 v[72:73], v[72:73], v[48:49], v[74:75]
	v_pk_fma_f32 v[70:71], v[70:71], v[46:47], v[76:77]
	s_nop 0
	v_cvt_pk_bf16_f32 v70, v70, v71
	v_cvt_pk_bf16_f32 v71, v72, v73
	global_store_dwordx2 v[82:83], v[70:71], off offset:256
	s_waitcnt vmcnt(3)
	v_lshlrev_b32_e32 v72, 16, v210
	v_and_b32_e32 v73, 0xffff0000, v210
	v_lshlrev_b32_e32 v70, 16, v211
	v_and_b32_e32 v71, 0xffff0000, v211
	v_pk_fma_f32 v[68:69], v[68:69], v[36:37], v[70:71]
	v_pk_fma_f32 v[66:67], v[66:67], v[34:35], v[72:73]
	s_nop 0
	v_cvt_pk_bf16_f32 v66, v66, v67
	v_cvt_pk_bf16_f32 v67, v68, v69
	global_store_dwordx2 v[82:83], v[66:67], off offset:288
	v_lshl_add_u64 v[66:67], v[146:147], 0, s[8:9]
	s_mov_b32 s8, 0x90000
	v_add_co_u32_e32 v68, vcc, s8, v146
	s_mov_b64 s[8:9], 0xa0000
	s_nop 0
	v_addc_co_u32_e32 v69, vcc, 0, v147, vcc
	global_load_dwordx2 v[70:71], v[68:69], off
	global_load_dwordx2 v[206:207], v[66:67], off offset:32
	global_load_dwordx2 v[208:209], v[66:67], off offset:256
	global_load_dwordx2 v[210:211], v[66:67], off offset:288
	s_waitcnt vmcnt(3)
	v_lshlrev_b32_e32 v72, 16, v70
	v_and_b32_e32 v73, 0xffff0000, v70
	v_lshlrev_b32_e32 v70, 16, v71
	v_and_b32_e32 v71, 0xffff0000, v71
	v_pk_fma_f32 v[60:61], v[60:61], v[64:65], v[70:71]
	v_pk_fma_f32 v[58:59], v[58:59], v[62:63], v[72:73]
	s_nop 0
	v_cvt_pk_bf16_f32 v58, v58, v59
	v_cvt_pk_bf16_f32 v59, v60, v61
	global_store_dwordx2 v[68:69], v[58:59], off
	s_waitcnt vmcnt(3)
	v_lshlrev_b32_e32 v60, 16, v206
	v_and_b32_e32 v61, 0xffff0000, v206
	v_lshlrev_b32_e32 v58, 16, v207
	v_and_b32_e32 v59, 0xffff0000, v207
	v_pk_fma_f32 v[52:53], v[52:53], v[56:57], v[58:59]
	v_pk_fma_f32 v[50:51], v[50:51], v[54:55], v[60:61]
	s_nop 0
	v_cvt_pk_bf16_f32 v50, v50, v51
	v_cvt_pk_bf16_f32 v51, v52, v53
	global_store_dwordx2 v[66:67], v[50:51], off offset:32
	s_waitcnt vmcnt(3)
; DI unsigned pk2(float a, float b) { f32x2 v = {a, b}; bfv2 r = __builtin_convertvector(v, bfv2); return __builtin_bit_cast(unsigned, r); }
; template <class Epi, class SchedT>
; DI void gemm_phase(LAS unsigned char* lds, const Gemm g, const SchedT& S, const Epi& E) {
;     ...
;         if (has_next) mk_voff();
;     DI void operator()(AccRef acc, const Unit& u, int wr, int wc, int fr, int fq) const {
;     ...
;         if (xb) {
; #pragma unroll
;             for (int ai = 0; ai < 2; ++ai)
; #pragma unroll
;                 for (int m = 0; m < 4; ++m) { const size_t off = (size_t)(row0 + wr * 64 + fr + ai * 128 + m * 16) * D + col0;
; #pragma unroll
;                     for (int bj = 0; bj < 2; ++bj)
; #pragma unroll
;                         for (int n = 0; n < 2; ++n) { const size_t o2 = off + bj * 128 + n * 16;
;                             const f32x4 r = bf4(*(const u32x2*)(xb + o2)) + gv[bj][n] * acc[ai][bj][m][n];
;                             u32x2 w; w.x = pk2(r[0], r[1]); w.y = pk2(r[2], r[3]); *(u32x2*)(out + o2) = w; }
;                     asm volatile("" ::: "memory"); }
	v_lshlrev_b32_e32 v52, 16, v208
	v_and_b32_e32 v53, 0xffff0000, v208
	v_lshlrev_b32_e32 v50, 16, v209
	v_and_b32_e32 v51, 0xffff0000, v209
	v_pk_fma_f32 v[44:45], v[44:45], v[48:49], v[50:51]
	v_pk_fma_f32 v[42:43], v[42:43], v[46:47], v[52:53]
	s_nop 0
	v_cvt_pk_bf16_f32 v42, v42, v43
	v_cvt_pk_bf16_f32 v43, v44, v45
	global_store_dwordx2 v[66:67], v[42:43], off offset:256
	s_waitcnt vmcnt(3)
	v_lshlrev_b32_e32 v44, 16, v210
	v_and_b32_e32 v45, 0xffff0000, v210
	v_lshlrev_b32_e32 v42, 16, v211
	v_and_b32_e32 v43, 0xffff0000, v211
	v_pk_fma_f32 v[40:41], v[40:41], v[36:37], v[42:43]
	v_pk_fma_f32 v[38:39], v[38:39], v[34:35], v[44:45]
	s_nop 0
	v_cvt_pk_bf16_f32 v38, v38, v39
	v_cvt_pk_bf16_f32 v39, v40, v41
	global_store_dwordx2 v[66:67], v[38:39], off offset:288
	v_lshl_add_u64 v[38:39], v[146:147], 0, s[8:9]
	s_mov_b32 s8, 0xa0000
	v_add_co_u32_e32 v40, vcc, s8, v146
	s_mov_b64 s[8:9], 0xb0000
	s_nop 0
	v_addc_co_u32_e32 v41, vcc, 0, v147, vcc
	global_load_dwordx2 v[42:43], v[40:41], off
	global_load_dwordx2 v[206:207], v[38:39], off offset:32
	global_load_dwordx2 v[208:209], v[38:39], off offset:256
	global_load_dwordx2 v[210:211], v[38:39], off offset:288
	s_waitcnt vmcnt(3)
	v_lshlrev_b32_e32 v44, 16, v42
	v_and_b32_e32 v45, 0xffff0000, v42
	v_lshlrev_b32_e32 v42, 16, v43
	v_and_b32_e32 v43, 0xffff0000, v43
	v_pk_fma_f32 v[32:33], v[32:33], v[64:65], v[42:43]
	v_pk_fma_f32 v[30:31], v[30:31], v[62:63], v[44:45]
	s_nop 0
	v_cvt_pk_bf16_f32 v30, v30, v31
	v_cvt_pk_bf16_f32 v31, v32, v33
	global_store_dwordx2 v[40:41], v[30:31], off
	s_waitcnt vmcnt(3)
	v_lshlrev_b32_e32 v32, 16, v206
	v_and_b32_e32 v33, 0xffff0000, v206
	v_lshlrev_b32_e32 v30, 16, v207
	v_and_b32_e32 v31, 0xffff0000, v207
	v_pk_fma_f32 v[28:29], v[28:29], v[56:57], v[30:31]
	v_pk_fma_f32 v[26:27], v[26:27], v[54:55], v[32:33]
	s_nop 0
	v_cvt_pk_bf16_f32 v26, v26, v27
	v_cvt_pk_bf16_f32 v27, v28, v29
	global_store_dwordx2 v[38:39], v[26:27], off offset:32
	s_waitcnt vmcnt(3)
	v_lshlrev_b32_e32 v28, 16, v208
	v_and_b32_e32 v29, 0xffff0000, v208
	v_lshlrev_b32_e32 v26, 16, v209
	v_and_b32_e32 v27, 0xffff0000, v209
	v_pk_fma_f32 v[24:25], v[24:25], v[48:49], v[26:27]
	v_pk_fma_f32 v[22:23], v[22:23], v[46:47], v[28:29]
	s_nop 0
	v_cvt_pk_bf16_f32 v22, v22, v23
	v_cvt_pk_bf16_f32 v23, v24, v25
	global_store_dwordx2 v[38:39], v[22:23], off offset:256
	s_waitcnt vmcnt(3)
	v_lshlrev_b32_e32 v24, 16, v210
	v_and_b32_e32 v25, 0xffff0000, v210
	v_lshlrev_b32_e32 v22, 16, v211
	v_and_b32_e32 v23, 0xffff0000, v211
	v_pk_fma_f32 v[20:21], v[20:21], v[36:37], v[22:23]
	v_pk_fma_f32 v[18:19], v[18:19], v[34:35], v[24:25]
	s_nop 0
	v_cvt_pk_bf16_f32 v18, v18, v19
	v_cvt_pk_bf16_f32 v19, v20, v21
	global_store_dwordx2 v[38:39], v[18:19], off offset:288
	v_lshl_add_u64 v[18:19], v[146:147], 0, s[8:9]
	s_mov_b32 s8, 0xb0000
	v_add_co_u32_e32 v20, vcc, s8, v146
	s_mov_b64 s[8:9], -1
	s_nop 0
	v_addc_co_u32_e32 v21, vcc, 0, v147, vcc
	global_load_dwordx2 v[22:23], v[20:21], off
	global_load_dwordx2 v[206:207], v[18:19], off offset:32
	global_load_dwordx2 v[208:209], v[18:19], off offset:256
	global_load_dwordx2 v[210:211], v[18:19], off offset:288
	s_and_b64 vcc, exec, s[2:3]
	s_waitcnt vmcnt(3)
	v_lshlrev_b32_e32 v24, 16, v22
	v_and_b32_e32 v25, 0xffff0000, v22
	v_lshlrev_b32_e32 v22, 16, v23
	v_and_b32_e32 v23, 0xffff0000, v23
	v_pk_fma_f32 v[16:17], v[16:17], v[64:65], v[22:23]
	v_pk_fma_f32 v[14:15], v[14:15], v[62:63], v[24:25]
	s_nop 0
	v_cvt_pk_bf16_f32 v14, v14, v15
	v_cvt_pk_bf16_f32 v15, v16, v17
	global_store_dwordx2 v[20:21], v[14:15], off
	s_waitcnt vmcnt(3)
	v_lshlrev_b32_e32 v16, 16, v206
	v_and_b32_e32 v17, 0xffff0000, v206
	v_lshlrev_b32_e32 v14, 16, v207
	v_and_b32_e32 v15, 0xffff0000, v207
	v_pk_fma_f32 v[12:13], v[12:13], v[56:57], v[14:15]
	v_pk_fma_f32 v[10:11], v[10:11], v[54:55], v[16:17]
	s_nop 0
	v_cvt_pk_bf16_f32 v10, v10, v11
	v_cvt_pk_bf16_f32 v11, v12, v13
	global_store_dwordx2 v[18:19], v[10:11], off offset:32
	s_waitcnt vmcnt(3)
	v_lshlrev_b32_e32 v12, 16, v208
	v_and_b32_e32 v13, 0xffff0000, v208
	v_lshlrev_b32_e32 v10, 16, v209
	v_and_b32_e32 v11, 0xffff0000, v209
	v_pk_fma_f32 v[8:9], v[8:9], v[48:49], v[10:11]
	v_pk_fma_f32 v[6:7], v[6:7], v[46:47], v[12:13]
	s_nop 0
	v_cvt_pk_bf16_f32 v6, v6, v7
	v_cvt_pk_bf16_f32 v7, v8, v9
	global_store_dwordx2 v[18:19], v[6:7], off offset:256
	s_waitcnt vmcnt(3)
	v_lshlrev_b32_e32 v8, 16, v210
	v_and_b32_e32 v9, 0xffff0000, v210
	v_lshlrev_b32_e32 v6, 16, v211
	v_and_b32_e32 v7, 0xffff0000, v211
	v_pk_fma_f32 v[4:5], v[4:5], v[36:37], v[6:7]
	v_pk_fma_f32 v[2:3], v[2:3], v[34:35], v[8:9]
	s_nop 0
	v_cvt_pk_bf16_f32 v2, v2, v3
	v_cvt_pk_bf16_f32 v3, v4, v5
	global_store_dwordx2 v[18:19], v[2:3], off offset:288
.Lg9_e_end:
	s_cbranch_vccz .LBB0_1697
	v_mov_b32_e32 v0, v192
	s_mov_b64 s[8:9], 0
	v_ashrrev_i32_e32 v3, 31, v0
	v_lshrrev_b32_e32 v3, 26, v3
	v_lshlrev_b32_e32 v2, 4, v0
	v_add_u32_e32 v3, v0, v3
	v_bfe_i32 v0, v0, 27, 1
	v_lshrrev_b32_e32 v0, 22, v0
	v_add_u32_e32 v0, v2, v0
	v_and_b32_e32 v0, 0xfffffc00, v0
	v_sub_u32_e32 v0, v2, v0
	v_lshrrev_b32_e32 v4, 4, v0
	v_bitop3_b32 v0, v4, v0, 32 bitop3:0x6c
	v_ashrrev_i32_e32 v5, 31, v0
	v_ashrrev_i32_e32 v3, 6, v3
	v_lshrrev_b32_e32 v5, 26, v5
	v_lshlrev_b32_e32 v4, 3, v3
	v_add_u32_e32 v5, v0, v5
	v_and_b32_e32 v4, 0x7ffff0, v4
	v_lshrrev_b32_e32 v6, 6, v5
	v_and_b32_e32 v5, 0xc0, v5
	v_add_u32_e32 v4, v6, v4
	v_sub_u32_e32 v0, v0, v5
	v_lshlrev_b32_e32 v3, 5, v3
	v_ashrrev_i16_sdwa v0, v200, sext(v0) dst_sel:DWORD dst_unused:UNUSED_PAD src0_sel:DWORD src1_sel:BYTE_0
	v_mul_lo_u32 v4, v4, s45
	v_bfe_i32 v0, v0, 0, 16
	v_and_or_b32 v3, v3, 32, v4
	v_add_u32_e32 v2, 0x2000, v2
	v_add_lshl_u32 v0, v3, v0, 1
	v_ashrrev_i32_e32 v3, 31, v2
	v_lshrrev_b32_e32 v3, 22, v3
	v_add_u32_e32 v3, v2, v3
	v_ashrrev_i32_e32 v3, 10, v3
	v_mul_i32_i24_e32 v4, 0x400, v3
	v_sub_u32_e32 v2, v2, v4
	v_lshrrev_b32_e32 v4, 4, v2
	v_bitop3_b32 v2, v4, v2, 32 bitop3:0x6c
	v_ashrrev_i32_e32 v5, 31, v2
	v_lshrrev_b32_e32 v5, 26, v5
	v_lshlrev_b32_e32 v4, 3, v3
	v_add_u32_e32 v5, v2, v5
	v_and_b32_e32 v4, 0x7ffff0, v4
	v_lshrrev_b32_e32 v6, 6, v5
	v_and_b32_e32 v5, 0xc0, v5
	v_add_u32_e32 v4, v6, v4
	v_sub_u32_e32 v2, v2, v5
	v_lshlrev_b32_e32 v3, 5, v3
	v_ashrrev_i16_sdwa v2, v200, sext(v2) dst_sel:DWORD dst_unused:UNUSED_PAD src0_sel:DWORD src1_sel:BYTE_0
	v_mul_lo_u32 v4, v4, s45
	v_bfe_i32 v2, v2, 0, 16
	v_and_or_b32 v3, v3, 32, v4
	v_add_lshl_u32 v34, v3, v2, 1
	s_branch .LBB0_1697

; __global__ void __launch_bounds__(NT) fwd_megakernel(Params p) {
;     extern __shared__ __attribute__((aligned(16))) unsigned char lds_raw[];
	.amdhsa_kernel _Z14fwd_megakernel6Params
		.amdhsa_group_segment_fixed_size 0
		.amdhsa_private_segment_fixed_size 0
		.amdhsa_kernarg_size 440
		.amdhsa_user_sgpr_count 2
		.amdhsa_user_sgpr_dispatch_ptr 0
		.amdhsa_user_sgpr_queue_ptr 0
		.amdhsa_user_sgpr_kernarg_segment_ptr 1
		.amdhsa_user_sgpr_dispatch_id 0
		.amdhsa_user_sgpr_kernarg_preload_length 0
		.amdhsa_user_sgpr_kernarg_preload_offset 0
		.amdhsa_user_sgpr_private_segment_size 0
		.amdhsa_uses_dynamic_stack 0
		.amdhsa_enable_private_segment 0
		.amdhsa_system_sgpr_workgroup_id_x 1
		.amdhsa_system_sgpr_workgroup_id_y 0
		.amdhsa_system_sgpr_workgroup_id_z 0
		.amdhsa_system_sgpr_workgroup_info 0
		.amdhsa_system_vgpr_workitem_id 2
		.amdhsa_next_free_vgpr 256
		.amdhsa_next_free_sgpr 102
		.amdhsa_accum_offset 256
		.amdhsa_reserve_vcc 1
		.amdhsa_float_round_mode_32 0
		.amdhsa_float_round_mode_16_64 0
		.amdhsa_float_denorm_mode_32 3
		.amdhsa_float_denorm_mode_16_64 3
		.amdhsa_dx10_clamp 1
		.amdhsa_ieee_mode 1
		.amdhsa_fp16_overflow 0
		.amdhsa_tg_split 0
		.amdhsa_exception_fp_ieee_invalid_op 0
		.amdhsa_exception_fp_denorm_src 0
		.amdhsa_exception_fp_ieee_div_zero 0
		.amdhsa_exception_fp_ieee_overflow 0
		.amdhsa_exception_fp_ieee_underflow 0
		.amdhsa_exception_fp_ieee_inexact 0
		.amdhsa_exception_int_div_zero 0
	.end_amdhsa_kernel

; __global__ void __launch_bounds__(NT) fwd_megakernel(Params p) {
;     extern __shared__ __attribute__((aligned(16))) unsigned char lds_raw[];
amdhsa.kernels:
  - .agpr_count:     0
    .args:
      - .offset:         0
        .size:           184
        .value_kind:     by_value
      - .offset:         184
        .size:           4
        .value_kind:     hidden_block_count_x
      - .offset:         188
        .size:           4
        .value_kind:     hidden_block_count_y
      - .offset:         192
        .size:           4
        .value_kind:     hidden_block_count_z
      - .offset:         196
        .size:           2
        .value_kind:     hidden_group_size_x
      - .offset:         198
        .size:           2
        .value_kind:     hidden_group_size_y
      - .offset:         200
        .size:           2
        .value_kind:     hidden_group_size_z
      - .offset:         202
        .size:           2
        .value_kind:     hidden_remainder_x
      - .offset:         204
        .size:           2
        .value_kind:     hidden_remainder_y
      - .offset:         206
        .size:           2
        .value_kind:     hidden_remainder_z
      - .offset:         224
        .size:           8
        .value_kind:     hidden_global_offset_x
      - .offset:         232
        .size:           8
        .value_kind:     hidden_global_offset_y
      - .offset:         240
        .size:           8
        .value_kind:     hidden_global_offset_z
      - .offset:         248
        .size:           2
        .value_kind:     hidden_grid_dims
      - .offset:         272
        .size:           8
        .value_kind:     hidden_multigrid_sync_arg
      - .offset:         304
        .size:           4
        .value_kind:     hidden_dynamic_lds_size
    .group_segment_fixed_size: 0
    .kernarg_segment_align: 8
    .kernarg_segment_size: 440
    .language:       OpenCL C
    .language_version:
      - 2
      - 0
    .max_flat_workgroup_size: 512
    .name:           _Z14fwd_megakernel6Params
    .private_segment_fixed_size: 0
    .sgpr_count:     108
    .sgpr_spill_count: 149
    .symbol:         _Z14fwd_megakernel6Params.kd
    .uniform_work_group_size: 1
    .uses_dynamic_stack: false
    .vgpr_count:     256
    .vgpr_spill_count: 0
    .wavefront_size: 64
